# v29 plus P0 w_merge_gate w_o_rnn w_out conversions moved to the tail of P1 interval
# baseline (speedup 1.0000x reference)
_Z8mega_fwd4Args:
	s_mov_b32 s100, 0
	s_mov_b32 s99, 0
	s_mov_b32 s98, 0
	s_mov_b32 s96, s2
	v_readfirstlane_b32 s2, v0
	s_lshr_b32 s2, s2, 6
	v_mbcnt_lo_u32_b32 v3, -1, 0
	v_mbcnt_hi_u32_b32 v3, -1, v3
	s_load_dword s15, s[0:1], 0xf8
	s_load_dwordx2 s[94:95], s[0:1], 0xe0
	s_load_dwordx4 s[4:7], s[0:1], 0xe8
	s_load_dwordx8 s[68:75], s[0:1], 0xc0
	v_writelane_b32 v254, s2, 0
	s_add_u32 s2, s0, 0xf8
	s_addc_u32 s3, s1, 0
	s_waitcnt lgkmcnt(0)
	v_writelane_b32 v254, s4, 1
	s_mov_b32 s10, s96
	s_nop 0
	v_writelane_b32 v254, s5, 2
	v_writelane_b32 v254, s6, 3
	v_writelane_b32 v254, s7, 4
	v_writelane_b32 v254, s2, 5
	s_nop 1
	v_writelane_b32 v254, s3, 6
	s_and_b32 s3, s15, 7
	s_mov_b32 s2, 0
	s_cmp_lg_u32 s3, 0
	s_cbranch_scc1 .LBB0_2
	s_ashr_i32 s4, s96, 31
	s_lshr_b32 s4, s4, 29
	s_add_i32 s4, s96, s4
	s_and_b32 s5, s4, -8
	s_ashr_i32 s3, s15, 3
	s_sub_i32 s5, s96, s5
	s_mul_i32 s3, s3, s5
	s_ashr_i32 s4, s4, 3
	s_add_i32 s10, s3, s4

.LBB0_18:
	s_cmp_eq_u32 s100, 0
	s_cbranch_scc0 .Lmy_c0_runB
	v_readlane_b32 s12, v254, 54
	v_readlane_b32 s13, v254, 55
	s_branch .LBB0_26

.LBB0_26:
	s_cmp_eq_u32 s100, 1
	s_cbranch_scc1 .LBB0_31
	s_cmpk_gt_i32 s12, 0xfff
	s_cbranch_scc1 .LBB0_31
	v_readlane_b32 s8, v254, 54
	v_readlane_b32 s9, v254, 55
	s_lshr_b32 s0, s9, 20
	s_add_i32 s4, s8, s0
	s_ashr_i32 s0, s4, 12
	s_ashr_i32 s1, s0, 31
	s_lshl_b64 s[0:1], s[0:1], 25
	s_add_u32 s5, s64, s0
	s_addc_u32 s6, s65, s1
	s_and_b32 s0, s4, 0xf000
	s_sub_i32 s4, s8, s0
	s_sext_i32_i16 s0, s4
	s_bfe_u32 s0, s0, 0x70018
	s_add_i32 s7, s4, s0
	s_sext_i32_i16 s0, s7
	s_ashr_i32 s0, s0, 7
	s_lshl_b32 s0, s0, 6
	s_ashr_i32 s1, s0, 31
	s_lshl_b64 s[0:1], s[0:1], 14
	s_add_u32 s5, s5, s0
	s_addc_u32 s6, s6, s1
	s_and_b32 s0, s7, 0xff80
	s_sub_i32 s0, s4, s0
	s_sext_i32_i16 s0, s0
	s_lshl_b32 s0, s0, 5
	s_ashr_i32 s1, s0, 31
	s_lshl_b64 s[0:1], s[0:1], 2
	s_add_u32 s0, s5, s0
	s_addc_u32 s1, s6, s1
	v_mov_b32_e32 v7, 0
	v_lshlrev_b32_e32 v6, 2, v0
	v_ashrrev_i32_e32 v5, 31, v4
	v_lshl_add_u64 v[8:9], s[0:1], 0, v[6:7]
	v_lshlrev_b64 v[10:11], 14, v[4:5]
	v_lshl_add_u64 v[18:19], v[8:9], 0, v[10:11]
	v_add_u32_e32 v10, 2, v4
	v_ashrrev_i32_e32 v11, 31, v10
	v_lshlrev_b64 v[12:13], 14, v[10:11]
	v_lshl_add_u64 v[20:21], v[8:9], 0, v[12:13]
	v_add_u32_e32 v12, 4, v4
	v_ashrrev_i32_e32 v13, 31, v12
	v_lshlrev_b64 v[14:15], 14, v[12:13]
	v_lshl_add_u64 v[22:23], v[8:9], 0, v[14:15]
	v_add_u32_e32 v14, 6, v4
	v_ashrrev_i32_e32 v15, 31, v14
	v_lshlrev_b64 v[16:17], 14, v[14:15]
	v_lshl_add_u64 v[24:25], v[8:9], 0, v[16:17]
	v_add_u32_e32 v16, 8, v4
	v_add_u32_e32 v28, 10, v4
	v_add_u32_e32 v32, 12, v4
	v_add_u32_e32 v36, 14, v4
	v_ashrrev_i32_e32 v17, 31, v16
	v_ashrrev_i32_e32 v29, 31, v28
	v_ashrrev_i32_e32 v33, 31, v32
	v_ashrrev_i32_e32 v37, 31, v36
	v_lshlrev_b64 v[26:27], 14, v[16:17]
	v_lshlrev_b64 v[30:31], 14, v[28:29]
	v_lshlrev_b64 v[34:35], 14, v[32:33]
	v_lshlrev_b64 v[38:39], 14, v[36:37]
	v_lshl_add_u64 v[26:27], v[8:9], 0, v[26:27]
	v_lshl_add_u64 v[30:31], v[8:9], 0, v[30:31]
	v_lshl_add_u64 v[34:35], v[8:9], 0, v[34:35]
	v_lshl_add_u64 v[38:39], v[8:9], 0, v[38:39]
	global_load_dword v65, v[18:19], off
	global_load_dword v84, v[20:21], off
	global_load_dword v85, v[22:23], off
	global_load_dword v86, v[24:25], off
	global_load_dword v87, v[26:27], off
	global_load_dword v88, v[30:31], off
	global_load_dword v89, v[34:35], off
	global_load_dword v90, v[38:39], off
	v_add_u32_e32 v24, 16, v4
	v_add_u32_e32 v40, 24, v4
	v_ashrrev_i32_e32 v25, 31, v24
	v_add_u32_e32 v26, 18, v4
	v_add_u32_e32 v30, 20, v4
	v_add_u32_e32 v34, 22, v4
	v_ashrrev_i32_e32 v41, 31, v40
	v_add_u32_e32 v44, 26, v4
	v_add_u32_e32 v48, 28, v4
	v_add_u32_e32 v52, 30, v4
	v_lshlrev_b64 v[18:19], 14, v[24:25]
	v_ashrrev_i32_e32 v27, 31, v26
	v_ashrrev_i32_e32 v31, 31, v30
	v_ashrrev_i32_e32 v35, 31, v34
	v_lshlrev_b64 v[42:43], 14, v[40:41]
	v_ashrrev_i32_e32 v45, 31, v44
	v_ashrrev_i32_e32 v49, 31, v48
	v_ashrrev_i32_e32 v53, 31, v52
	v_lshl_add_u64 v[18:19], v[8:9], 0, v[18:19]
	v_lshlrev_b64 v[20:21], 14, v[26:27]
	v_lshlrev_b64 v[22:23], 14, v[30:31]
	v_lshlrev_b64 v[38:39], 14, v[34:35]
	v_lshl_add_u64 v[42:43], v[8:9], 0, v[42:43]
	v_lshlrev_b64 v[46:47], 14, v[44:45]
	v_lshlrev_b64 v[50:51], 14, v[48:49]
	v_lshlrev_b64 v[54:55], 14, v[52:53]
	v_lshl_add_u64 v[20:21], v[8:9], 0, v[20:21]
	v_lshl_add_u64 v[22:23], v[8:9], 0, v[22:23]
	v_lshl_add_u64 v[38:39], v[8:9], 0, v[38:39]
	v_lshl_add_u64 v[46:47], v[8:9], 0, v[46:47]
	v_lshl_add_u64 v[50:51], v[8:9], 0, v[50:51]
	v_lshl_add_u64 v[54:55], v[8:9], 0, v[54:55]
	global_load_dword v91, v[18:19], off
	global_load_dword v92, v[20:21], off
	global_load_dword v93, v[22:23], off
	global_load_dword v94, v[38:39], off
	global_load_dword v95, v[42:43], off
	global_load_dword v96, v[46:47], off
	global_load_dword v97, v[50:51], off
	global_load_dword v98, v[54:55], off
	v_add_u32_e32 v42, 32, v4
	v_add_u32_e32 v56, 40, v4
	v_ashrrev_i32_e32 v43, 31, v42
	v_add_u32_e32 v46, 34, v4
	v_add_u32_e32 v50, 36, v4
	v_add_u32_e32 v54, 38, v4
	v_ashrrev_i32_e32 v57, 31, v56
	v_add_u32_e32 v60, 42, v4
	v_add_u32_e32 v66, 44, v4
	v_add_u32_e32 v70, 46, v4
	v_lshlrev_b64 v[18:19], 14, v[42:43]
	v_ashrrev_i32_e32 v47, 31, v46
	v_ashrrev_i32_e32 v51, 31, v50
	v_ashrrev_i32_e32 v55, 31, v54
	v_lshlrev_b64 v[58:59], 14, v[56:57]
	v_ashrrev_i32_e32 v61, 31, v60
	v_ashrrev_i32_e32 v67, 31, v66
	v_ashrrev_i32_e32 v71, 31, v70
	v_lshl_add_u64 v[18:19], v[8:9], 0, v[18:19]
	v_lshlrev_b64 v[20:21], 14, v[46:47]
	v_lshlrev_b64 v[22:23], 14, v[50:51]
	v_lshlrev_b64 v[38:39], 14, v[54:55]
	v_lshl_add_u64 v[58:59], v[8:9], 0, v[58:59]
	v_lshlrev_b64 v[62:63], 14, v[60:61]
	v_lshlrev_b64 v[68:69], 14, v[66:67]
	v_lshlrev_b64 v[72:73], 14, v[70:71]
	v_lshl_add_u64 v[20:21], v[8:9], 0, v[20:21]
	v_lshl_add_u64 v[22:23], v[8:9], 0, v[22:23]
	v_lshl_add_u64 v[38:39], v[8:9], 0, v[38:39]
	v_lshl_add_u64 v[62:63], v[8:9], 0, v[62:63]
	v_lshl_add_u64 v[68:69], v[8:9], 0, v[68:69]
	v_lshl_add_u64 v[72:73], v[8:9], 0, v[72:73]
	global_load_dword v106, v[18:19], off
	global_load_dword v107, v[20:21], off
	global_load_dword v116, v[22:23], off
	global_load_dword v117, v[38:39], off
	global_load_dword v118, v[58:59], off
	global_load_dword v119, v[62:63], off
	global_load_dword v120, v[68:69], off
	global_load_dword v121, v[72:73], off
	v_add_u32_e32 v58, 48, v4
	v_ashrrev_i32_e32 v59, 31, v58
	v_add_u32_e32 v62, 50, v4
	v_add_u32_e32 v68, 52, v4
	v_add_u32_e32 v72, 54, v4
	v_add_u32_e32 v74, 56, v4
	v_add_u32_e32 v78, 58, v4
	v_add_u32_e32 v82, 60, v4
	v_add_u32_e32 v102, 62, v4
	v_lshlrev_b64 v[18:19], 14, v[58:59]
	v_ashrrev_i32_e32 v63, 31, v62
	v_ashrrev_i32_e32 v69, 31, v68
	v_ashrrev_i32_e32 v73, 31, v72
	v_ashrrev_i32_e32 v75, 31, v74
	v_ashrrev_i32_e32 v79, 31, v78
	v_ashrrev_i32_e32 v83, 31, v82
	v_ashrrev_i32_e32 v103, 31, v102
	v_lshl_add_u64 v[18:19], v[8:9], 0, v[18:19]
	v_lshlrev_b64 v[20:21], 14, v[62:63]
	v_lshlrev_b64 v[22:23], 14, v[68:69]
	v_lshlrev_b64 v[38:39], 14, v[72:73]
	v_lshlrev_b64 v[76:77], 14, v[74:75]
	v_lshlrev_b64 v[80:81], 14, v[78:79]
	v_lshlrev_b64 v[100:101], 14, v[82:83]
	v_lshlrev_b64 v[104:105], 14, v[102:103]
	v_lshl_add_u64 v[20:21], v[8:9], 0, v[20:21]
	v_lshl_add_u64 v[22:23], v[8:9], 0, v[22:23]
	v_lshl_add_u64 v[38:39], v[8:9], 0, v[38:39]
	v_lshl_add_u64 v[76:77], v[8:9], 0, v[76:77]
	v_lshl_add_u64 v[80:81], v[8:9], 0, v[80:81]
	v_lshl_add_u64 v[100:101], v[8:9], 0, v[100:101]
	v_lshl_add_u64 v[8:9], v[8:9], 0, v[104:105]
	global_load_dword v138, v[18:19], off
	global_load_dword v139, v[20:21], off
	global_load_dword v140, v[22:23], off
	global_load_dword v141, v[38:39], off
	global_load_dword v142, v[76:77], off
	global_load_dword v143, v[80:81], off
	global_load_dword v144, v[100:101], off
	global_load_dword v145, v[8:9], off
	v_lshlrev_b64 v[20:21], 12, v[32:33]
	v_lshlrev_b64 v[32:33], 12, v[40:41]
	v_lshlrev_b64 v[40:41], 12, v[42:43]
	v_lshlrev_b64 v[42:43], 12, v[46:47]
	v_lshlrev_b64 v[46:47], 12, v[54:55]
	v_lshlrev_b64 v[54:55], 12, v[70:71]
	v_lshlrev_b64 v[70:71], 12, v[82:83]
	v_add_u32_e32 v83, s77, v6
	v_and_b32_e32 v6, 56, v1
	v_lshlrev_b64 v[8:9], 12, v[4:5]
	v_mul_u32_u24_e32 v3, 0x84, v6
	v_lshlrev_b32_e32 v5, 2, v2
	s_movk_i32 s0, 0x84
	v_add3_u32 v5, s77, v3, v5
	v_ashrrev_i32_e32 v3, 31, v2
	v_lshlrev_b64 v[38:39], 12, v[52:53]
	v_lshlrev_b64 v[52:53], 12, v[66:67]
	v_lshlrev_b64 v[66:67], 12, v[74:75]
	v_mul_lo_u32 v99, v4, s0
	v_lshlrev_b64 v[74:75], 12, v[2:3]
	s_mov_b64 s[0:1], 0x8000
	v_lshl_add_u64 v[76:77], v[74:75], 0, s[0:1]
	s_mov_b64 s[0:1], 0x10000
	v_lshlrev_b64 v[18:19], 12, v[28:29]
	v_lshlrev_b64 v[28:29], 12, v[30:31]
	v_lshlrev_b64 v[30:31], 12, v[34:35]
	v_lshlrev_b64 v[34:35], 12, v[44:45]
	v_lshlrev_b64 v[44:45], 12, v[50:51]
	v_lshlrev_b64 v[50:51], 12, v[60:61]
	v_lshlrev_b64 v[60:61], 12, v[68:69]
	v_lshlrev_b64 v[68:69], 12, v[78:79]
	v_lshl_add_u64 v[78:79], v[74:75], 0, s[0:1]
	s_mov_b64 s[0:1], 0x18000
	v_lshlrev_b64 v[10:11], 12, v[10:11]
	v_lshlrev_b64 v[12:13], 12, v[12:13]
	v_lshlrev_b64 v[14:15], 12, v[14:15]
	v_lshlrev_b64 v[16:17], 12, v[16:17]
	v_lshlrev_b64 v[22:23], 12, v[36:37]
	v_lshlrev_b64 v[24:25], 12, v[24:25]
	v_lshlrev_b64 v[26:27], 12, v[26:27]
	v_lshlrev_b64 v[36:37], 12, v[48:49]
	v_lshlrev_b64 v[48:49], 12, v[56:57]
	v_lshlrev_b64 v[56:57], 12, v[58:59]
	v_lshlrev_b64 v[58:59], 12, v[62:63]
	v_lshlrev_b64 v[62:63], 12, v[72:73]
	v_lshlrev_b64 v[72:73], 12, v[102:103]
	v_lshl_add_u64 v[80:81], v[74:75], 0, s[0:1]
	v_lshlrev_b32_e32 v82, 2, v0
	v_add_u32_e32 v3, v83, v99
	v_lshlrev_b32_e32 v6, 1, v6
	s_movk_i32 s4, 0x7fff
	s_mov_b32 s5, 0xffff0000
	s_mov_b32 s7, s8
	s_branch .LBB0_29

.LBB0_31:
	s_cmp_eq_u32 s100, 0
	s_cbranch_scc1 .LBB0_40
	s_andn2_b64 vcc, exec, s[78:79]
	s_cbranch_vccnz .LBB0_40
	v_readlane_b32 s0, v254, 43
	v_readlane_b32 s1, v254, 44
	s_add_u32 s0, s66, s0
	s_addc_u32 s1, s67, s1
	v_readlane_b32 s4, v254, 45
	v_readlane_b32 s5, v254, 46
	s_add_u32 s4, s0, s4
	s_addc_u32 s5, s1, s5
	v_readlane_b32 s0, v254, 47
	v_readlane_b32 s1, v254, 48
	s_lshl_b64 s[0:1], s[0:1], 2
	s_add_u32 s4, s4, s0
	s_addc_u32 s5, s5, s1
	v_mov_b32_e32 v7, 0
	v_lshlrev_b32_e32 v6, 2, v0
	v_ashrrev_i32_e32 v5, 31, v4
	v_lshl_add_u64 v[8:9], s[4:5], 0, v[6:7]
	v_lshlrev_b64 v[10:11], 14, v[4:5]
	v_lshl_add_u64 v[18:19], v[8:9], 0, v[10:11]
	v_add_u32_e32 v10, 2, v4
	v_ashrrev_i32_e32 v11, 31, v10
	v_lshlrev_b64 v[12:13], 14, v[10:11]
	v_lshl_add_u64 v[20:21], v[8:9], 0, v[12:13]
	v_add_u32_e32 v12, 4, v4
	v_ashrrev_i32_e32 v13, 31, v12
	v_lshlrev_b64 v[14:15], 14, v[12:13]
	v_lshl_add_u64 v[22:23], v[8:9], 0, v[14:15]
	v_add_u32_e32 v14, 6, v4
	v_ashrrev_i32_e32 v15, 31, v14
	v_lshlrev_b64 v[16:17], 14, v[14:15]
	v_lshl_add_u64 v[24:25], v[8:9], 0, v[16:17]
	v_add_u32_e32 v16, 8, v4
	v_add_u32_e32 v28, 10, v4
	v_add_u32_e32 v32, 12, v4
	v_add_u32_e32 v36, 14, v4
	v_ashrrev_i32_e32 v17, 31, v16
	v_ashrrev_i32_e32 v29, 31, v28
	v_ashrrev_i32_e32 v33, 31, v32
	v_ashrrev_i32_e32 v37, 31, v36
	v_lshlrev_b64 v[26:27], 14, v[16:17]
	v_lshlrev_b64 v[30:31], 14, v[28:29]
	v_lshlrev_b64 v[34:35], 14, v[32:33]
	v_lshlrev_b64 v[38:39], 14, v[36:37]
	v_lshl_add_u64 v[26:27], v[8:9], 0, v[26:27]
	v_lshl_add_u64 v[30:31], v[8:9], 0, v[30:31]
	v_lshl_add_u64 v[34:35], v[8:9], 0, v[34:35]
	v_lshl_add_u64 v[38:39], v[8:9], 0, v[38:39]
	global_load_dword v78, v[18:19], off
	global_load_dword v79, v[20:21], off
	global_load_dword v80, v[22:23], off
	global_load_dword v81, v[24:25], off
	global_load_dword v82, v[26:27], off
	global_load_dword v83, v[30:31], off
	global_load_dword v84, v[34:35], off
	global_load_dword v85, v[38:39], off
	v_add_u32_e32 v24, 16, v4
	v_add_u32_e32 v40, 24, v4
	v_ashrrev_i32_e32 v25, 31, v24
	v_add_u32_e32 v26, 18, v4
	v_add_u32_e32 v30, 20, v4
	v_add_u32_e32 v34, 22, v4
	v_ashrrev_i32_e32 v41, 31, v40
	v_add_u32_e32 v44, 26, v4
	v_add_u32_e32 v48, 28, v4
	v_add_u32_e32 v52, 30, v4
	v_lshlrev_b64 v[18:19], 14, v[24:25]
	v_ashrrev_i32_e32 v27, 31, v26
	v_ashrrev_i32_e32 v31, 31, v30
	v_ashrrev_i32_e32 v35, 31, v34
	v_lshlrev_b64 v[42:43], 14, v[40:41]
	v_ashrrev_i32_e32 v45, 31, v44
	v_ashrrev_i32_e32 v49, 31, v48
	v_ashrrev_i32_e32 v53, 31, v52
	v_lshl_add_u64 v[18:19], v[8:9], 0, v[18:19]
	v_lshlrev_b64 v[20:21], 14, v[26:27]
	v_lshlrev_b64 v[22:23], 14, v[30:31]
	v_lshlrev_b64 v[38:39], 14, v[34:35]
	v_lshl_add_u64 v[42:43], v[8:9], 0, v[42:43]
	v_lshlrev_b64 v[46:47], 14, v[44:45]
	v_lshlrev_b64 v[50:51], 14, v[48:49]
	v_lshlrev_b64 v[54:55], 14, v[52:53]
	v_lshl_add_u64 v[20:21], v[8:9], 0, v[20:21]
	v_lshl_add_u64 v[22:23], v[8:9], 0, v[22:23]
	v_lshl_add_u64 v[38:39], v[8:9], 0, v[38:39]
	v_lshl_add_u64 v[46:47], v[8:9], 0, v[46:47]
	v_lshl_add_u64 v[50:51], v[8:9], 0, v[50:51]
	v_lshl_add_u64 v[54:55], v[8:9], 0, v[54:55]
	global_load_dword v86, v[18:19], off
	global_load_dword v87, v[20:21], off
	global_load_dword v88, v[22:23], off
	global_load_dword v89, v[38:39], off
	global_load_dword v90, v[42:43], off
	global_load_dword v91, v[46:47], off
	global_load_dword v92, v[50:51], off
	global_load_dword v93, v[54:55], off
	v_add_u32_e32 v42, 32, v4
	v_add_u32_e32 v56, 40, v4
	v_ashrrev_i32_e32 v43, 31, v42
	v_add_u32_e32 v46, 34, v4
	v_add_u32_e32 v50, 36, v4
	v_add_u32_e32 v54, 38, v4
	v_ashrrev_i32_e32 v57, 31, v56
	v_add_u32_e32 v60, 42, v4
	v_add_u32_e32 v66, 44, v4
	v_add_u32_e32 v70, 46, v4
	v_lshlrev_b64 v[18:19], 14, v[42:43]
	v_ashrrev_i32_e32 v47, 31, v46
	v_ashrrev_i32_e32 v51, 31, v50
	v_ashrrev_i32_e32 v55, 31, v54
	v_lshlrev_b64 v[58:59], 14, v[56:57]
	v_ashrrev_i32_e32 v61, 31, v60
	v_ashrrev_i32_e32 v67, 31, v66
	v_ashrrev_i32_e32 v71, 31, v70
	v_lshl_add_u64 v[18:19], v[8:9], 0, v[18:19]
	v_lshlrev_b64 v[20:21], 14, v[46:47]
	v_lshlrev_b64 v[22:23], 14, v[50:51]
	v_lshlrev_b64 v[38:39], 14, v[54:55]
	v_lshl_add_u64 v[58:59], v[8:9], 0, v[58:59]
	v_lshlrev_b64 v[62:63], 14, v[60:61]
	v_lshlrev_b64 v[68:69], 14, v[66:67]
	v_lshlrev_b64 v[72:73], 14, v[70:71]
	v_lshl_add_u64 v[20:21], v[8:9], 0, v[20:21]
	v_lshl_add_u64 v[22:23], v[8:9], 0, v[22:23]
	v_lshl_add_u64 v[38:39], v[8:9], 0, v[38:39]
	v_lshl_add_u64 v[62:63], v[8:9], 0, v[62:63]
	v_lshl_add_u64 v[68:69], v[8:9], 0, v[68:69]
	v_lshl_add_u64 v[72:73], v[8:9], 0, v[72:73]
	global_load_dword v102, v[18:19], off
	global_load_dword v103, v[20:21], off
	global_load_dword v112, v[22:23], off
	global_load_dword v113, v[38:39], off
	global_load_dword v114, v[58:59], off
	global_load_dword v115, v[62:63], off
	global_load_dword v116, v[68:69], off
	global_load_dword v117, v[72:73], off
	v_add_u32_e32 v58, 48, v4
	v_ashrrev_i32_e32 v59, 31, v58
	v_add_u32_e32 v62, 50, v4
	v_add_u32_e32 v68, 52, v4
	v_add_u32_e32 v72, 54, v4
	v_add_u32_e32 v74, 56, v4
	v_add_u32_e32 v94, 58, v4
	v_add_u32_e32 v98, 60, v4
	v_add_u32_e32 v104, 62, v4
	v_lshlrev_b64 v[18:19], 14, v[58:59]
	v_ashrrev_i32_e32 v63, 31, v62
	v_ashrrev_i32_e32 v69, 31, v68
	v_ashrrev_i32_e32 v73, 31, v72
	v_ashrrev_i32_e32 v75, 31, v74
	v_ashrrev_i32_e32 v95, 31, v94
	v_ashrrev_i32_e32 v99, 31, v98
	v_ashrrev_i32_e32 v105, 31, v104
	v_lshl_add_u64 v[18:19], v[8:9], 0, v[18:19]
	v_lshlrev_b64 v[20:21], 14, v[62:63]
	v_lshlrev_b64 v[22:23], 14, v[68:69]
	v_lshlrev_b64 v[38:39], 14, v[72:73]
	v_lshlrev_b64 v[76:77], 14, v[74:75]
	v_lshlrev_b64 v[96:97], 14, v[94:95]
	v_lshlrev_b64 v[100:101], 14, v[98:99]
	v_lshlrev_b64 v[106:107], 14, v[104:105]
	v_lshl_add_u64 v[20:21], v[8:9], 0, v[20:21]
	v_lshl_add_u64 v[22:23], v[8:9], 0, v[22:23]
	v_lshl_add_u64 v[38:39], v[8:9], 0, v[38:39]
	v_lshl_add_u64 v[76:77], v[8:9], 0, v[76:77]
	v_lshl_add_u64 v[96:97], v[8:9], 0, v[96:97]
	v_lshl_add_u64 v[100:101], v[8:9], 0, v[100:101]
	v_lshl_add_u64 v[8:9], v[8:9], 0, v[106:107]
	global_load_dword v134, v[18:19], off
	global_load_dword v135, v[20:21], off
	global_load_dword v136, v[22:23], off
	global_load_dword v137, v[38:39], off
	global_load_dword v138, v[76:77], off
	global_load_dword v139, v[96:97], off
	global_load_dword v140, v[100:101], off
	global_load_dword v141, v[8:9], off
	v_add_u32_e32 v65, s77, v6
	v_and_b32_e32 v6, 56, v1
	v_mul_u32_u24_e32 v1, 0x84, v6
	v_lshlrev_b32_e32 v3, 2, v2
	s_movk_i32 s4, 0x84
	v_add3_u32 v1, s77, v1, v3
	v_ashrrev_i32_e32 v3, 31, v2
	v_lshlrev_b64 v[18:19], 12, v[28:29]
	v_lshlrev_b64 v[28:29], 12, v[30:31]
	v_lshlrev_b64 v[30:31], 12, v[34:35]
	v_lshlrev_b64 v[34:35], 12, v[44:45]
	v_lshlrev_b64 v[44:45], 12, v[50:51]
	v_lshlrev_b64 v[50:51], 12, v[60:61]
	v_lshlrev_b64 v[60:61], 12, v[68:69]
	v_lshlrev_b64 v[68:69], 12, v[94:95]
	v_mul_lo_u32 v94, v4, s4
	v_lshlrev_b64 v[2:3], 13, v[2:3]
	s_mov_b64 s[4:5], 0x10000
	v_lshlrev_b64 v[8:9], 12, v[4:5]
	v_lshl_add_u64 v[4:5], v[2:3], 0, s[4:5]
	s_mov_b64 s[4:5], 0x20000
	v_lshlrev_b64 v[38:39], 12, v[52:53]
	v_lshlrev_b64 v[52:53], 12, v[66:67]
	v_lshlrev_b64 v[66:67], 12, v[74:75]
	v_lshl_add_u64 v[74:75], v[2:3], 0, s[4:5]
	s_mov_b64 s[4:5], 0x30000
	v_lshl_add_u64 v[76:77], v[2:3], 0, s[4:5]
	v_readlane_b32 s4, v254, 54
	v_lshlrev_b64 v[10:11], 12, v[10:11]
	v_lshlrev_b64 v[12:13], 12, v[12:13]
	v_lshlrev_b64 v[14:15], 12, v[14:15]
	v_lshlrev_b64 v[16:17], 12, v[16:17]
	v_lshlrev_b64 v[20:21], 12, v[32:33]
	v_lshlrev_b64 v[22:23], 12, v[36:37]
	v_lshlrev_b64 v[24:25], 12, v[24:25]
	v_lshlrev_b64 v[26:27], 12, v[26:27]
	v_lshlrev_b64 v[32:33], 12, v[40:41]
	v_lshlrev_b64 v[36:37], 12, v[48:49]
	v_lshlrev_b64 v[40:41], 12, v[42:43]
	v_lshlrev_b64 v[42:43], 12, v[46:47]
	v_lshlrev_b64 v[46:47], 12, v[54:55]
	v_lshlrev_b64 v[48:49], 12, v[56:57]
	v_lshlrev_b64 v[54:55], 12, v[70:71]
	v_lshlrev_b64 v[56:57], 12, v[58:59]
	v_lshlrev_b64 v[58:59], 12, v[62:63]
	v_lshlrev_b64 v[62:63], 12, v[72:73]
	v_lshlrev_b64 v[70:71], 12, v[98:99]
	v_lshlrev_b64 v[72:73], 12, v[104:105]
	v_lshlrev_b32_e32 v6, 1, v6
	s_movk_i32 s6, 0x7fff
	s_mov_b32 s7, 0xffff0000
	v_add_u32_e32 v65, v65, v94
	s_mov_b32 s9, s4
	v_readlane_b32 s5, v254, 55
	s_branch .LBB0_34

.LBB0_40:
	s_cmp_eq_u32 s100, 1
	s_cbranch_scc0 .Lmy_c0_norm40
	s_mov_b32 s100, 2
	v_readlane_b32 s0, v255, 10
	v_readlane_b32 s1, v255, 11
	v_readlane_b32 s4, v255, 12
	v_readlane_b32 s5, v255, 13
	v_readlane_b32 s6, v255, 14
	v_readlane_b32 s7, v255, 15
	v_readlane_b32 s8, v255, 16
	v_readlane_b32 s9, v255, 17
	v_readlane_b32 s10, v255, 18
	v_readlane_b32 s11, v255, 19
	v_readlane_b32 s12, v255, 20
	v_readlane_b32 s13, v255, 21
	v_readlane_b32 s16, v255, 22
	v_readlane_b32 s17, v255, 23
	v_readlane_b32 s18, v255, 24
	v_readlane_b32 s19, v255, 25
	v_readlane_b32 s21, v255, 26
	v_readlane_b32 s23, v255, 27
	v_readlane_b32 s24, v255, 28
	v_readlane_b32 s25, v255, 29
	v_readlane_b32 s26, v255, 30
	v_readlane_b32 s27, v255, 31
	v_readlane_b32 s28, v255, 32
	v_readlane_b32 s29, v255, 33
	v_readlane_b32 s30, v255, 34
	v_readlane_b32 s31, v255, 35
	s_branch .LBB0_172

.LBB0_172:
	s_cmp_eq_u32 s100, 0
	s_cbranch_scc0 .Lmy_c0_norm172
	s_mov_b32 s100, 1
	v_writelane_b32 v255, s0, 10
	v_writelane_b32 v255, s1, 11
	v_writelane_b32 v255, s4, 12
	v_writelane_b32 v255, s5, 13
	v_writelane_b32 v255, s6, 14
	v_writelane_b32 v255, s7, 15
	v_writelane_b32 v255, s8, 16
	v_writelane_b32 v255, s9, 17
	v_writelane_b32 v255, s10, 18
	v_writelane_b32 v255, s11, 19
	v_writelane_b32 v255, s12, 20
	v_writelane_b32 v255, s13, 21
	v_writelane_b32 v255, s16, 22
	v_writelane_b32 v255, s17, 23
	v_writelane_b32 v255, s18, 24
	v_writelane_b32 v255, s19, 25
	v_writelane_b32 v255, s21, 26
	v_writelane_b32 v255, s23, 27
	v_writelane_b32 v255, s24, 28
	v_writelane_b32 v255, s25, 29
	v_writelane_b32 v255, s26, 30
	v_writelane_b32 v255, s27, 31
	v_writelane_b32 v255, s28, 32
	v_writelane_b32 v255, s29, 33
	v_writelane_b32 v255, s30, 34
	v_writelane_b32 v255, s31, 35
	v_mbcnt_lo_u32_b32 v64, -1, 0
	v_mbcnt_hi_u32_b32 v64, -1, v64
	s_nop 0
	v_ashrrev_i32_e32 v4, 5, v64
	v_and_b32_e32 v0, 31, v64
	v_ashrrev_i32_e32 v2, 3, v64
	v_lshlrev_b32_e32 v1, 3, v64
	v_readlane_b32 s66, v254, 5
	v_readlane_b32 s67, v254, 6
	s_sub_u32 s66, s66, 0x80
	s_subb_u32 s67, s67, 0
	s_load_dwordx2 s[66:67], s[66:67], 0x0
	s_waitcnt lgkmcnt(0)
	s_branch .LBB0_18
